# prep1 xg: 20 rows per half-workgroup (5 per wave) over 410 non-bias half-workgroups
# speedup vs baseline: 1.0110x; 1.0012x over previous
.Lxg6_w:
	s_cmp_lt_i32 s52, 0
	s_cbranch_scc1 .Lxg6_end
	s_cmpk_gt_i32 s52, 0x199
	s_cbranch_scc1 .Lxg6_end
	v_lshrrev_b32_e32 v0, 6, v229
	s_nop 0
	v_readfirstlane_b32 s53, v0
	s_nop 3
	s_lshl_b32 s52, s52, 2
	s_add_i32 s52, s52, s53
	s_cmpk_gt_i32 s52, 0x667
	s_cbranch_scc1 .Lxg6_end
	v_readlane_b32 s40, v254, 5
	v_readlane_b32 s41, v254, 6
	v_readlane_b32 s42, v254, 7
	v_readlane_b32 s43, v254, 8
	v_readlane_b32 s54, v255, 7
	v_readlane_b32 s55, v255, 8
	s_nop 3
	s_cmpk_lt_i32 s52, 0x334
	s_cbranch_scc0 .Lxg6_smp
	s_mul_i32 s44, s52, 5
	s_movk_i32 s45, 0xfff
	s_mov_b32 s46, 0
	s_mov_b32 s47, 0
	s_mov_b64 s[48:49], s[40:41]
	s_branch .Lxg6_seg
.Lxg6_smp:
	s_sub_i32 s52, s52, 0x334
	s_mov_b32 s47, 0
	s_cmpk_lt_i32 s52, 0xcd
	s_cbranch_scc1 .Lxg6_sg
	s_sub_i32 s52, s52, 0xcd
	s_add_i32 s47, s47, 1
	s_cmpk_lt_i32 s52, 0xcd
	s_cbranch_scc1 .Lxg6_sg
	s_sub_i32 s52, s52, 0xcd
	s_add_i32 s47, s47, 1
	s_cmpk_lt_i32 s52, 0xcd
	s_cbranch_scc1 .Lxg6_sg
	s_sub_i32 s52, s52, 0xcd
	s_add_i32 s47, s47, 1
.Lxg6_sg:
	s_lshl_b32 s45, s47, 10
	s_add_i32 s45, s45, 0x1000
	s_mul_i32 s44, s52, 5
	s_add_i32 s44, s44, s45
	s_add_i32 s45, s45, 0x3ff
	s_movk_i32 s46, 0x1000
	s_add_i32 s47, s47, 1
	s_mov_b64 s[48:49], s[42:43]
.Lxg6_seg:
	s_mul_i32 s53, s47, 0x6000
	s_add_u32 s50, s54, s53
	s_addc_u32 s51, s55, 0
	s_add_u32 s50, s50, 0x1000
	s_addc_u32 s51, s51, 0
	v_lshrrev_b32_e32 v18, 1, v200
	v_lshrrev_b32_e32 v19, 2, v200
	s_add_i32 s2, s44, 0
	s_min_i32 s2, s2, s45
	s_sub_i32 s3, s2, s46
	s_lshl_b32 s3, s3, 12
	v_add_u32_e32 v48, s3, v200
	s_lshl_b32 s3, s2, 11
	v_add_u32_e32 v54, s3, v18
	s_lshl_b32 s3, s2, 7
	v_add_u32_e32 v60, s3, v19
	s_add_i32 s2, s44, 1
	s_min_i32 s2, s2, s45
	s_sub_i32 s3, s2, s46
	s_lshl_b32 s3, s3, 12
	v_add_u32_e32 v49, s3, v200
	s_lshl_b32 s3, s2, 11
	v_add_u32_e32 v55, s3, v18
	s_lshl_b32 s3, s2, 7
	v_add_u32_e32 v61, s3, v19
	s_add_i32 s2, s44, 2
	s_min_i32 s2, s2, s45
	s_sub_i32 s3, s2, s46
	s_lshl_b32 s3, s3, 12
	v_add_u32_e32 v50, s3, v200
	s_lshl_b32 s3, s2, 11
	v_add_u32_e32 v56, s3, v18
	s_lshl_b32 s3, s2, 7
	v_add_u32_e32 v62, s3, v19
	s_add_i32 s2, s44, 3
	s_min_i32 s2, s2, s45
	s_sub_i32 s3, s2, s46
	s_lshl_b32 s3, s3, 12
	v_add_u32_e32 v51, s3, v200
	s_lshl_b32 s3, s2, 11
	v_add_u32_e32 v57, s3, v18
	s_lshl_b32 s3, s2, 7
	v_add_u32_e32 v63, s3, v19
	s_add_i32 s2, s44, 4
	s_min_i32 s2, s2, s45
	s_sub_i32 s3, s2, s46
	s_lshl_b32 s3, s3, 12
	v_add_u32_e32 v52, s3, v200
	s_lshl_b32 s3, s2, 11
	v_add_u32_e32 v58, s3, v18
	s_lshl_b32 s3, s2, 7
	v_add_u32_e32 v16, s3, v19
	global_load_dwordx4 v[20:23], v[128:129], off
	global_load_dwordx4 v[24:27], v[128:129], off offset:1024
	global_load_dwordx4 v[28:31], v[128:129], off offset:2048
	global_load_dwordx4 v[32:35], v[128:129], off offset:3072
	global_load_dwordx4 v[146:149], v200, s[50:51]
	global_load_dwordx4 v[150:153], v200, s[50:51] offset:1024
	global_load_dwordx4 v[154:157], v200, s[50:51] offset:2048
	global_load_dwordx4 v[158:161], v200, s[50:51] offset:3072
	global_load_dwordx4 v[64:67], v48, s[48:49]
	global_load_dwordx4 v[68:71], v48, s[48:49] offset:1024
	global_load_dwordx4 v[72:75], v48, s[48:49] offset:2048
	global_load_dwordx4 v[76:79], v48, s[48:49] offset:3072
	global_load_dwordx4 v[80:83], v49, s[48:49]
	global_load_dwordx4 v[84:87], v49, s[48:49] offset:1024
	global_load_dwordx4 v[88:91], v49, s[48:49] offset:2048
	global_load_dwordx4 v[92:95], v49, s[48:49] offset:3072
	global_load_dwordx4 v[96:99], v50, s[48:49]
	global_load_dwordx4 v[100:103], v50, s[48:49] offset:1024
	global_load_dwordx4 v[104:107], v50, s[48:49] offset:2048
	global_load_dwordx4 v[108:111], v50, s[48:49] offset:3072
	global_load_dwordx4 v[112:115], v51, s[48:49]
	global_load_dwordx4 v[116:119], v51, s[48:49] offset:1024
	global_load_dwordx4 v[120:123], v51, s[48:49] offset:2048
	global_load_dwordx4 v[124:127], v51, s[48:49] offset:3072
	global_load_dwordx4 v[162:165], v52, s[48:49]
	global_load_dwordx4 v[166:169], v52, s[48:49] offset:1024
	global_load_dwordx4 v[170:173], v52, s[48:49] offset:2048
	global_load_dwordx4 v[174:177], v52, s[48:49] offset:3072
	s_waitcnt vmcnt(20)
	v_pk_add_f32 v[146:147], v[146:147], 1.0 op_sel_hi:[1,0]
	v_pk_add_f32 v[148:149], v[148:149], 1.0 op_sel_hi:[1,0]
	v_pk_add_f32 v[150:151], v[150:151], 1.0 op_sel_hi:[1,0]
	v_pk_add_f32 v[152:153], v[152:153], 1.0 op_sel_hi:[1,0]
	v_pk_add_f32 v[154:155], v[154:155], 1.0 op_sel_hi:[1,0]
	v_pk_add_f32 v[156:157], v[156:157], 1.0 op_sel_hi:[1,0]
	v_pk_add_f32 v[158:159], v[158:159], 1.0 op_sel_hi:[1,0]
	v_pk_add_f32 v[160:161], v[160:161], 1.0 op_sel_hi:[1,0]
	s_waitcnt vmcnt(16)
	v_mul_f32_e32 v12, v65, v65
	v_fmac_f32_e32 v12, v64, v64
	v_fmac_f32_e32 v12, v66, v66
	v_fmac_f32_e32 v12, v67, v67
	v_mul_f32_e32 v13, v69, v69
	v_fmac_f32_e32 v13, v68, v68
	v_fmac_f32_e32 v13, v70, v70
	v_fmac_f32_e32 v13, v71, v71
	v_mul_f32_e32 v14, v73, v73
	v_fmac_f32_e32 v14, v72, v72
	v_fmac_f32_e32 v14, v74, v74
	v_fmac_f32_e32 v14, v75, v75
	v_mul_f32_e32 v15, v77, v77
	v_fmac_f32_e32 v15, v76, v76
	v_fmac_f32_e32 v15, v78, v78
	v_fmac_f32_e32 v15, v79, v79
	v_add_f32_e32 v36, v12, v13
	v_add_f32_e32 v36, v36, v14
	v_add_f32_e32 v36, v36, v15
	v_pk_mul_f32 v[64:65], v[64:65], v[20:21]
	v_pk_mul_f32 v[66:67], v[66:67], v[22:23]
	v_pk_mul_f32 v[64:65], v[64:65], v[146:147]
	v_pk_mul_f32 v[66:67], v[66:67], v[148:149]
	v_cvt_pk_bf16_f32 v64, v64, v65
	v_cvt_pk_bf16_f32 v65, v66, v67
	v_pk_mul_f32 v[68:69], v[68:69], v[24:25]
	v_pk_mul_f32 v[70:71], v[70:71], v[26:27]
	v_pk_mul_f32 v[68:69], v[68:69], v[150:151]
	v_pk_mul_f32 v[70:71], v[70:71], v[152:153]
	v_cvt_pk_bf16_f32 v68, v68, v69
	v_cvt_pk_bf16_f32 v69, v70, v71
	v_pk_mul_f32 v[72:73], v[72:73], v[28:29]
	v_pk_mul_f32 v[74:75], v[74:75], v[30:31]
	v_pk_mul_f32 v[72:73], v[72:73], v[154:155]
	v_pk_mul_f32 v[74:75], v[74:75], v[156:157]
	v_cvt_pk_bf16_f32 v72, v72, v73
	v_cvt_pk_bf16_f32 v73, v74, v75
	v_pk_mul_f32 v[76:77], v[76:77], v[32:33]
	v_pk_mul_f32 v[78:79], v[78:79], v[34:35]
	v_pk_mul_f32 v[76:77], v[76:77], v[158:159]
	v_pk_mul_f32 v[78:79], v[78:79], v[160:161]
	v_cvt_pk_bf16_f32 v76, v76, v77
	v_cvt_pk_bf16_f32 v77, v78, v79
	global_store_dwordx2 v54, v[64:65], s[14:15]
	global_store_dwordx2 v54, v[68:69], s[14:15] offset:512
	global_store_dwordx2 v54, v[72:73], s[14:15] offset:1024
	global_store_dwordx2 v54, v[76:77], s[14:15] offset:1536
	s_waitcnt vmcnt(16)
	v_mul_f32_e32 v12, v81, v81
	v_fmac_f32_e32 v12, v80, v80
	v_fmac_f32_e32 v12, v82, v82
	v_fmac_f32_e32 v12, v83, v83
	v_mul_f32_e32 v13, v85, v85
	v_fmac_f32_e32 v13, v84, v84
	v_fmac_f32_e32 v13, v86, v86
	v_fmac_f32_e32 v13, v87, v87
	v_mul_f32_e32 v14, v89, v89
	v_fmac_f32_e32 v14, v88, v88
	v_fmac_f32_e32 v14, v90, v90
	v_fmac_f32_e32 v14, v91, v91
	v_mul_f32_e32 v15, v93, v93
	v_fmac_f32_e32 v15, v92, v92
	v_fmac_f32_e32 v15, v94, v94
	v_fmac_f32_e32 v15, v95, v95
	v_add_f32_e32 v37, v12, v13
	v_add_f32_e32 v37, v37, v14
	v_add_f32_e32 v37, v37, v15
	v_pk_mul_f32 v[80:81], v[80:81], v[20:21]
	v_pk_mul_f32 v[82:83], v[82:83], v[22:23]
	v_pk_mul_f32 v[80:81], v[80:81], v[146:147]
	v_pk_mul_f32 v[82:83], v[82:83], v[148:149]
	v_cvt_pk_bf16_f32 v80, v80, v81
	v_cvt_pk_bf16_f32 v81, v82, v83
	v_pk_mul_f32 v[84:85], v[84:85], v[24:25]
	v_pk_mul_f32 v[86:87], v[86:87], v[26:27]
	v_pk_mul_f32 v[84:85], v[84:85], v[150:151]
	v_pk_mul_f32 v[86:87], v[86:87], v[152:153]
	v_cvt_pk_bf16_f32 v84, v84, v85
	v_cvt_pk_bf16_f32 v85, v86, v87
	v_pk_mul_f32 v[88:89], v[88:89], v[28:29]
	v_pk_mul_f32 v[90:91], v[90:91], v[30:31]
	v_pk_mul_f32 v[88:89], v[88:89], v[154:155]
	v_pk_mul_f32 v[90:91], v[90:91], v[156:157]
	v_cvt_pk_bf16_f32 v88, v88, v89
	v_cvt_pk_bf16_f32 v89, v90, v91
	v_pk_mul_f32 v[92:93], v[92:93], v[32:33]
	v_pk_mul_f32 v[94:95], v[94:95], v[34:35]
	v_pk_mul_f32 v[92:93], v[92:93], v[158:159]
	v_pk_mul_f32 v[94:95], v[94:95], v[160:161]
	v_cvt_pk_bf16_f32 v92, v92, v93
	v_cvt_pk_bf16_f32 v93, v94, v95
	global_store_dwordx2 v55, v[80:81], s[14:15]
	global_store_dwordx2 v55, v[84:85], s[14:15] offset:512
	global_store_dwordx2 v55, v[88:89], s[14:15] offset:1024
	global_store_dwordx2 v55, v[92:93], s[14:15] offset:1536
	s_waitcnt vmcnt(16)
	v_mul_f32_e32 v12, v97, v97
	v_fmac_f32_e32 v12, v96, v96
	v_fmac_f32_e32 v12, v98, v98
	v_fmac_f32_e32 v12, v99, v99
	v_mul_f32_e32 v13, v101, v101
	v_fmac_f32_e32 v13, v100, v100
	v_fmac_f32_e32 v13, v102, v102
	v_fmac_f32_e32 v13, v103, v103
	v_mul_f32_e32 v14, v105, v105
	v_fmac_f32_e32 v14, v104, v104
	v_fmac_f32_e32 v14, v106, v106
	v_fmac_f32_e32 v14, v107, v107
	v_mul_f32_e32 v15, v109, v109
	v_fmac_f32_e32 v15, v108, v108
	v_fmac_f32_e32 v15, v110, v110
	v_fmac_f32_e32 v15, v111, v111
	v_add_f32_e32 v38, v12, v13
	v_add_f32_e32 v38, v38, v14
	v_add_f32_e32 v38, v38, v15
	v_pk_mul_f32 v[96:97], v[96:97], v[20:21]
	v_pk_mul_f32 v[98:99], v[98:99], v[22:23]
	v_pk_mul_f32 v[96:97], v[96:97], v[146:147]
	v_pk_mul_f32 v[98:99], v[98:99], v[148:149]
	v_cvt_pk_bf16_f32 v96, v96, v97
	v_cvt_pk_bf16_f32 v97, v98, v99
	v_pk_mul_f32 v[100:101], v[100:101], v[24:25]
	v_pk_mul_f32 v[102:103], v[102:103], v[26:27]
	v_pk_mul_f32 v[100:101], v[100:101], v[150:151]
	v_pk_mul_f32 v[102:103], v[102:103], v[152:153]
	v_cvt_pk_bf16_f32 v100, v100, v101
	v_cvt_pk_bf16_f32 v101, v102, v103
	v_pk_mul_f32 v[104:105], v[104:105], v[28:29]
	v_pk_mul_f32 v[106:107], v[106:107], v[30:31]
	v_pk_mul_f32 v[104:105], v[104:105], v[154:155]
	v_pk_mul_f32 v[106:107], v[106:107], v[156:157]
	v_cvt_pk_bf16_f32 v104, v104, v105
	v_cvt_pk_bf16_f32 v105, v106, v107
	v_pk_mul_f32 v[108:109], v[108:109], v[32:33]
	v_pk_mul_f32 v[110:111], v[110:111], v[34:35]
	v_pk_mul_f32 v[108:109], v[108:109], v[158:159]
	v_pk_mul_f32 v[110:111], v[110:111], v[160:161]
	v_cvt_pk_bf16_f32 v108, v108, v109
	v_cvt_pk_bf16_f32 v109, v110, v111
	global_store_dwordx2 v56, v[96:97], s[14:15]
	global_store_dwordx2 v56, v[100:101], s[14:15] offset:512
	global_store_dwordx2 v56, v[104:105], s[14:15] offset:1024
	global_store_dwordx2 v56, v[108:109], s[14:15] offset:1536
	s_waitcnt vmcnt(16)
	v_mul_f32_e32 v12, v113, v113
	v_fmac_f32_e32 v12, v112, v112
	v_fmac_f32_e32 v12, v114, v114
	v_fmac_f32_e32 v12, v115, v115
	v_mul_f32_e32 v13, v117, v117
	v_fmac_f32_e32 v13, v116, v116
	v_fmac_f32_e32 v13, v118, v118
	v_fmac_f32_e32 v13, v119, v119
	v_mul_f32_e32 v14, v121, v121
	v_fmac_f32_e32 v14, v120, v120
	v_fmac_f32_e32 v14, v122, v122
	v_fmac_f32_e32 v14, v123, v123
	v_mul_f32_e32 v15, v125, v125
	v_fmac_f32_e32 v15, v124, v124
	v_fmac_f32_e32 v15, v126, v126
	v_fmac_f32_e32 v15, v127, v127
	v_add_f32_e32 v39, v12, v13
	v_add_f32_e32 v39, v39, v14
	v_add_f32_e32 v39, v39, v15
	v_pk_mul_f32 v[112:113], v[112:113], v[20:21]
	v_pk_mul_f32 v[114:115], v[114:115], v[22:23]
	v_pk_mul_f32 v[112:113], v[112:113], v[146:147]
	v_pk_mul_f32 v[114:115], v[114:115], v[148:149]
	v_cvt_pk_bf16_f32 v112, v112, v113
	v_cvt_pk_bf16_f32 v113, v114, v115
	v_pk_mul_f32 v[116:117], v[116:117], v[24:25]
	v_pk_mul_f32 v[118:119], v[118:119], v[26:27]
	v_pk_mul_f32 v[116:117], v[116:117], v[150:151]
	v_pk_mul_f32 v[118:119], v[118:119], v[152:153]
	v_cvt_pk_bf16_f32 v116, v116, v117
	v_cvt_pk_bf16_f32 v117, v118, v119
	v_pk_mul_f32 v[120:121], v[120:121], v[28:29]
	v_pk_mul_f32 v[122:123], v[122:123], v[30:31]
	v_pk_mul_f32 v[120:121], v[120:121], v[154:155]
	v_pk_mul_f32 v[122:123], v[122:123], v[156:157]
	v_cvt_pk_bf16_f32 v120, v120, v121
	v_cvt_pk_bf16_f32 v121, v122, v123
	v_pk_mul_f32 v[124:125], v[124:125], v[32:33]
	v_pk_mul_f32 v[126:127], v[126:127], v[34:35]
	v_pk_mul_f32 v[124:125], v[124:125], v[158:159]
	v_pk_mul_f32 v[126:127], v[126:127], v[160:161]
	v_cvt_pk_bf16_f32 v124, v124, v125
	v_cvt_pk_bf16_f32 v125, v126, v127
	global_store_dwordx2 v57, v[112:113], s[14:15]
	global_store_dwordx2 v57, v[116:117], s[14:15] offset:512
	global_store_dwordx2 v57, v[120:121], s[14:15] offset:1024
	global_store_dwordx2 v57, v[124:125], s[14:15] offset:1536
	s_waitcnt vmcnt(16)
	v_mul_f32_e32 v12, v163, v163
	v_fmac_f32_e32 v12, v162, v162
	v_fmac_f32_e32 v12, v164, v164
	v_fmac_f32_e32 v12, v165, v165
	v_mul_f32_e32 v13, v167, v167
	v_fmac_f32_e32 v13, v166, v166
	v_fmac_f32_e32 v13, v168, v168
	v_fmac_f32_e32 v13, v169, v169
	v_mul_f32_e32 v14, v171, v171
	v_fmac_f32_e32 v14, v170, v170
	v_fmac_f32_e32 v14, v172, v172
	v_fmac_f32_e32 v14, v173, v173
	v_mul_f32_e32 v15, v175, v175
	v_fmac_f32_e32 v15, v174, v174
	v_fmac_f32_e32 v15, v176, v176
	v_fmac_f32_e32 v15, v177, v177
	v_add_f32_e32 v40, v12, v13
	v_add_f32_e32 v40, v40, v14
	v_add_f32_e32 v40, v40, v15
	v_pk_mul_f32 v[162:163], v[162:163], v[20:21]
	v_pk_mul_f32 v[164:165], v[164:165], v[22:23]
	v_pk_mul_f32 v[162:163], v[162:163], v[146:147]
	v_pk_mul_f32 v[164:165], v[164:165], v[148:149]
	v_cvt_pk_bf16_f32 v162, v162, v163
	v_cvt_pk_bf16_f32 v163, v164, v165
	v_pk_mul_f32 v[166:167], v[166:167], v[24:25]
	v_pk_mul_f32 v[168:169], v[168:169], v[26:27]
	v_pk_mul_f32 v[166:167], v[166:167], v[150:151]
	v_pk_mul_f32 v[168:169], v[168:169], v[152:153]
	v_cvt_pk_bf16_f32 v166, v166, v167
	v_cvt_pk_bf16_f32 v167, v168, v169
	v_pk_mul_f32 v[170:171], v[170:171], v[28:29]
	v_pk_mul_f32 v[172:173], v[172:173], v[30:31]
	v_pk_mul_f32 v[170:171], v[170:171], v[154:155]
	v_pk_mul_f32 v[172:173], v[172:173], v[156:157]
	v_cvt_pk_bf16_f32 v170, v170, v171
	v_cvt_pk_bf16_f32 v171, v172, v173
	v_pk_mul_f32 v[174:175], v[174:175], v[32:33]
	v_pk_mul_f32 v[176:177], v[176:177], v[34:35]
	v_pk_mul_f32 v[174:175], v[174:175], v[158:159]
	v_pk_mul_f32 v[176:177], v[176:177], v[160:161]
	v_cvt_pk_bf16_f32 v174, v174, v175
	v_cvt_pk_bf16_f32 v175, v176, v177
	global_store_dwordx2 v58, v[162:163], s[14:15]
	global_store_dwordx2 v58, v[166:167], s[14:15] offset:512
	global_store_dwordx2 v58, v[170:171], s[14:15] offset:1024
	global_store_dwordx2 v58, v[174:175], s[14:15] offset:1536
	ds_bpermute_b32 v42, v4, v36
	ds_bpermute_b32 v43, v4, v37
	ds_bpermute_b32 v44, v4, v38
	ds_bpermute_b32 v45, v4, v39
	ds_bpermute_b32 v46, v4, v40
	s_waitcnt lgkmcnt(0)
	v_add_f32_e32 v36, v36, v42
	v_add_f32_e32 v37, v37, v43
	v_add_f32_e32 v38, v38, v44
	v_add_f32_e32 v39, v39, v45
	v_add_f32_e32 v40, v40, v46
	ds_bpermute_b32 v42, v5, v36
	ds_bpermute_b32 v43, v5, v37
	ds_bpermute_b32 v44, v5, v38
	ds_bpermute_b32 v45, v5, v39
	ds_bpermute_b32 v46, v5, v40
	s_waitcnt lgkmcnt(0)
	v_add_f32_e32 v36, v36, v42
	v_add_f32_e32 v37, v37, v43
	v_add_f32_e32 v38, v38, v44
	v_add_f32_e32 v39, v39, v45
	v_add_f32_e32 v40, v40, v46
	ds_bpermute_b32 v42, v6, v36
	ds_bpermute_b32 v43, v6, v37
	ds_bpermute_b32 v44, v6, v38
	ds_bpermute_b32 v45, v6, v39
	ds_bpermute_b32 v46, v6, v40
	s_waitcnt lgkmcnt(0)
	v_add_f32_e32 v36, v36, v42
	v_add_f32_e32 v37, v37, v43
	v_add_f32_e32 v38, v38, v44
	v_add_f32_e32 v39, v39, v45
	v_add_f32_e32 v40, v40, v46
	ds_bpermute_b32 v42, v7, v36
	ds_bpermute_b32 v43, v7, v37
	ds_bpermute_b32 v44, v7, v38
	ds_bpermute_b32 v45, v7, v39
	ds_bpermute_b32 v46, v7, v40
	s_waitcnt lgkmcnt(0)
	v_add_f32_e32 v36, v36, v42
	v_add_f32_e32 v37, v37, v43
	v_add_f32_e32 v38, v38, v44
	v_add_f32_e32 v39, v39, v45
	v_add_f32_e32 v40, v40, v46
	ds_bpermute_b32 v42, v8, v36
	ds_bpermute_b32 v43, v8, v37
	ds_bpermute_b32 v44, v8, v38
	ds_bpermute_b32 v45, v8, v39
	ds_bpermute_b32 v46, v8, v40
	s_waitcnt lgkmcnt(0)
	v_add_f32_e32 v36, v36, v42
	v_add_f32_e32 v37, v37, v43
	v_add_f32_e32 v38, v38, v44
	v_add_f32_e32 v39, v39, v45
	v_add_f32_e32 v40, v40, v46
	ds_bpermute_b32 v42, v9, v36
	ds_bpermute_b32 v43, v9, v37
	ds_bpermute_b32 v44, v9, v38
	ds_bpermute_b32 v45, v9, v39
	ds_bpermute_b32 v46, v9, v40
	s_waitcnt lgkmcnt(0)
	v_add_f32_e32 v36, v36, v42
	v_add_f32_e32 v37, v37, v43
	v_add_f32_e32 v38, v38, v44
	v_add_f32_e32 v39, v39, v45
	v_add_f32_e32 v40, v40, v46
	s_and_saveexec_b64 s[2:3], s[36:37]
	v_cndmask_b32_e64 v36, 0, v36, s[38:39]
	v_cndmask_b32_e64 v37, 0, v37, s[38:39]
	v_cndmask_b32_e64 v38, 0, v38, s[38:39]
	v_cndmask_b32_e64 v39, 0, v39, s[38:39]
	v_cndmask_b32_e64 v40, 0, v40, s[38:39]
	global_store_dword v60, v36, s[16:17]
	global_store_dword v61, v37, s[16:17]
	global_store_dword v62, v38, s[16:17]
	global_store_dword v63, v39, s[16:17]
	global_store_dword v16, v40, s[16:17]
	s_or_b64 exec, exec, s[2:3]
